# P3 weight-transposes: the 32 row-scale loads of w_uq / w_ukv items batched into one round trip (was 16 serialized pairs), on top of the in-proj epilogue rinv batching
# speedup vs baseline: 1.0202x; 1.0004x over previous
; DI void transpose_item(int g_wave, LAS unsigned char* lds, const float* src, int K, int Nsrc, bf16_t* dst, int job, const float* rscale, int kt, int ntile) {
;     ...
;         for (int kk = 0; kk < 32; ++kk) { const int k = kt * 64 + k0 + 2 * kk; v[kk] = ns >= 0 ? src[(size_t)k * Nsrc + ns] : 0.f; }
;         if (rscale) {
; #pragma unroll
;             for (int kk = 0; kk < 32; ++kk) v[kk] *= rscale[kt * 64 + k0 + 2 * kk];
;         }
.LBB0_590:
	s_or_b64 exec, exec, s[8:9]
	s_and_b64 s[2:3], s[2:3], exec
	v_readlane_b32 s2, v253, 54
	s_cselect_b32 s7, s2, 0
	v_readlane_b32 s2, v253, 55
	s_cselect_b32 s8, s2, 0
	s_and_b64 s[2:3], s[4:5], exec
	v_readlane_b32 s2, v253, 53
	s_cselect_b32 s3, s2, s8
	v_readlane_b32 s2, v253, 52
	s_cselect_b32 s2, s2, s7
	s_cmp_lg_u64 s[2:3], 0
	s_cbranch_scc0 .LBB0_467
	v_lshl_add_u64 v[16:17], v[16:17], 2, s[2:3]
	global_load_dword v150, v[16:17], off
	global_load_dword v151, v[16:17], off offset:8
	global_load_dword v152, v[16:17], off offset:16
	global_load_dword v153, v[16:17], off offset:24
	global_load_dword v154, v[16:17], off offset:32
	global_load_dword v155, v[16:17], off offset:40
	global_load_dword v156, v[16:17], off offset:48
	global_load_dword v157, v[16:17], off offset:56
	global_load_dword v158, v[16:17], off offset:64
	global_load_dword v159, v[16:17], off offset:72
	global_load_dword v160, v[16:17], off offset:80
	global_load_dword v161, v[16:17], off offset:88
	global_load_dword v162, v[16:17], off offset:96
	global_load_dword v163, v[16:17], off offset:104
	global_load_dword v164, v[16:17], off offset:112
	global_load_dword v165, v[16:17], off offset:120
	global_load_dword v166, v[16:17], off offset:128
	global_load_dword v167, v[16:17], off offset:136
	global_load_dword v168, v[16:17], off offset:144
	global_load_dword v169, v[16:17], off offset:152
	global_load_dword v170, v[16:17], off offset:160
	global_load_dword v171, v[16:17], off offset:168
	global_load_dword v172, v[16:17], off offset:176
	global_load_dword v173, v[16:17], off offset:184
	global_load_dword v174, v[16:17], off offset:192
	global_load_dword v175, v[16:17], off offset:200
	global_load_dword v176, v[16:17], off offset:208
	global_load_dword v177, v[16:17], off offset:216
	global_load_dword v178, v[16:17], off offset:224
	global_load_dword v179, v[16:17], off offset:232
	global_load_dword v180, v[16:17], off offset:240
	global_load_dword v181, v[16:17], off offset:248
	s_waitcnt vmcnt(30)
	v_pk_mul_f32 v[0:1], v[0:1], v[150:151]
	s_waitcnt vmcnt(28)
	v_pk_mul_f32 v[2:3], v[2:3], v[152:153]
	s_waitcnt vmcnt(26)
	v_pk_mul_f32 v[4:5], v[4:5], v[154:155]
	s_waitcnt vmcnt(24)
	v_pk_mul_f32 v[6:7], v[6:7], v[156:157]
	s_waitcnt vmcnt(22)
	v_pk_mul_f32 v[8:9], v[8:9], v[158:159]
	s_waitcnt vmcnt(20)
	v_pk_mul_f32 v[10:11], v[10:11], v[160:161]
	s_waitcnt vmcnt(18)
	v_pk_mul_f32 v[12:13], v[12:13], v[162:163]
	s_waitcnt vmcnt(16)
	v_pk_mul_f32 v[14:15], v[14:15], v[164:165]
	s_waitcnt vmcnt(14)
	v_pk_mul_f32 v[18:19], v[18:19], v[166:167]
	s_waitcnt vmcnt(12)
	v_pk_mul_f32 v[20:21], v[20:21], v[168:169]
	s_waitcnt vmcnt(10)
	v_pk_mul_f32 v[24:25], v[24:25], v[170:171]
	s_waitcnt vmcnt(8)
	v_pk_mul_f32 v[26:27], v[26:27], v[172:173]
	s_waitcnt vmcnt(6)
	v_pk_mul_f32 v[28:29], v[28:29], v[174:175]
	s_waitcnt vmcnt(4)
	v_pk_mul_f32 v[30:31], v[30:31], v[176:177]
	s_waitcnt vmcnt(2)
	v_pk_mul_f32 v[32:33], v[32:33], v[178:179]
	s_waitcnt vmcnt(0)
	v_pk_mul_f32 v[34:35], v[34:35], v[180:181]
	s_branch .LBB0_467
